# tail in-proj GEMM staged by LDS-DMA (global_load_lds_dwordx4) into an XOR-swizzled unpadded LDS image, no register staging or ds_write
# speedup vs baseline: 1.0004x; 1.0004x over previous
; DI f32x4 mfma16(bf16x8 a, bf16x8 b, f32x4 c) { return __builtin_amdgcn_mfma_f32_16x16x32_bf16(a, b, c, 0, 0, 0); }
; #define GLOAD0(kt) { GL(xa0, ag, lda, voa, 0, kt); GL(xa1, ag, lda, voa, 1, kt); GL(xa2, ag, lda, voa, 2, kt); GL(xa3, ag, lda, voa, 3, kt); GL(xb0, bg, ldb, vob, 0, kt); GL(xb1, bg, ldb, vob, 1, kt); GL(xb2, bg, ldb, vob, 2, kt); GL(xb3, bg, ldb, vob, 3, kt); }
; DI void gemm_block(f32x4 (&acc)[4][4], const u16* Ap, int lda, const u16* Bp, int ldb, int K, char* lds, int tid, bool swap_w1 = false) {
;   const int lane = tid & 63, q = lane >> 4, jn = lane & 15;
;   const int wave = __builtin_amdgcn_readfirstlane(tid >> 6), wa = wave >> 1, wb = wave & 1;
;   uint4 xa0, xa1, xa2, xa3, xb0, xb1, xb2, xb3;
;   uint4 ya0, ya1, ya2, ya3, yb0, yb1, yb2, yb3;
;   const int srow = tid >> 3, scol = tid & 7;
;   const unsigned voa = (unsigned)(srow * lda + scol * 8) * 2u, vob = (unsigned)(srow * ldb + scol * 8) * 2u;
;   const char* ag = reinterpret_cast<const char*>(Ap);
;   const char* bg = reinterpret_cast<const char*>(Bp);
;   char* st0 = lds + (srow * GROW + scol * 8) * 2;
;   const bool sw = swap_w1 && (wa == 1);
;   const char* a0p = sw ? (lds + G_TILE_BYTES + (wb * 64 + jn) * GROW * 2 + q * 16) : (lds + (wa * 64 + jn) * GROW * 2 + q * 16);
;   const char* b0p = sw ? (lds + (wa * 64 + jn) * GROW * 2 + q * 16) : (lds + G_TILE_BYTES + (wb * 64 + jn) * GROW * 2 + q * 16);
;     ...
;   auto compute = [&](int buf) {
; #pragma unroll
;     for (int ks = 0; ks < 2; ++ks) {
;       bf16x8 a[4], b[4];
; #pragma unroll
;       for (int i = 0; i < 4; ++i) a[i] = *reinterpret_cast<const bf16x8*>(a0p + buf * G_BUF_BYTES + i * 16 * GROW * 2 + ks * 64);
; #pragma unroll
;       for (int j = 0; j < 4; ++j) b[j] = *reinterpret_cast<const bf16x8*>(b0p + buf * G_BUF_BYTES + j * 16 * GROW * 2 + ks * 64);
;       __builtin_amdgcn_s_setprio(1);
; #pragma unroll
;       for (int i = 0; i < 4; ++i)
; #pragma unroll
;         for (int j = 0; j < 4; ++j) acc[i][j] = mfma16(a[i], b[j], acc[i][j]);
;       __builtin_amdgcn_s_setprio(0);
;     }
;   };
;   const int nkt = K >> 6;
;   GLOAD0(0);
;   GLOAD1(1);
;   GSTORE0(0);
;   __syncthreads();
.LBB0_961:
	s_mov_b32 s0, s17
	s_lshl_b32 s0, s0, 7
	s_ashr_i32 s1, s0, 31
	s_lshl_b64 s[40:41], s[0:1], 11
	s_add_u32 s18, s34, s40
	v_readlane_b32 s1, v250, 19
	s_addc_u32 s19, s1, s41
	v_readlane_b32 s1, v250, 20
	s_add_u32 s20, s1, s40
	v_readlane_b32 s1, v250, 21
	s_addc_u32 s21, s1, s41
	v_readlane_b32 s1, v250, 22
	s_add_u32 s22, s1, s40
	v_readlane_b32 s1, v250, 23
	s_addc_u32 s23, s1, s41
	v_readlane_b32 s1, v250, 24
	s_add_u32 s24, s1, s40
	v_readlane_b32 s1, v250, 25
	s_addc_u32 s25, s1, s41
	v_readlane_b32 s1, v250, 26
	s_add_u32 s26, s1, s40
	v_readlane_b32 s1, v250, 27
	s_addc_u32 s27, s1, s41
	v_readlane_b32 s1, v250, 28
	s_add_u32 s28, s1, s40
	v_readlane_b32 s1, v250, 29
	s_addc_u32 s29, s1, s41
	v_readlane_b32 s1, v250, 30
	s_add_u32 s38, s1, s40
	v_readlane_b32 s1, v250, 31
	s_addc_u32 s39, s1, s41
	v_readlane_b32 s1, v250, 32
	s_add_u32 s40, s1, s40
	v_readlane_b32 s1, v250, 33
	s_addc_u32 s41, s1, s41
	s_sub_u32 s26, s26, 0x100
	s_subb_u32 s27, s27, 0
	s_sub_u32 s40, s40, 0x100
	s_subb_u32 s41, s41, 0
	s_sub_u32 s38, s38, 0x100
	s_subb_u32 s39, s39, 0
	s_sub_u32 s28, s28, 0x100
	s_subb_u32 s29, s29, 0
	s_sub_u32 s24, s24, 0x100
	s_subb_u32 s25, s25, 0
	s_sub_u32 s22, s22, 0x100
	s_subb_u32 s23, s23, 0
	s_sub_u32 s20, s20, 0x100
	s_subb_u32 s21, s21, 0
	s_sub_u32 s18, s18, 0x100
	s_subb_u32 s19, s19, 0
	s_mov_b64 s[42:43], s[2:3]
	s_mov_b32 s1, 0
	v_and_b32_e32 v32, 15, v130
	v_bfe_u32 v33, v130, 4, 2
	v_bfe_u32 v34, v130, 1, 3
	v_xor_b32_e32 v33, v33, v34
	v_lshlrev_b32_e32 v33, 4, v33
	v_lshl_or_b32 v32, v32, 7, v33
	v_lshrrev_b32_e32 v34, 7, v130
	v_lshl_or_b32 v28, v34, 13, v32
	v_xor_b32_e32 v29, 64, v28
	v_bfe_u32 v34, v130, 6, 1
	v_lshl_or_b32 v30, v34, 13, v32
	v_add_u32_e32 v30, 0x4000, v30
	v_xor_b32_e32 v31, 64, v30
	v_bfe_u32 v34, v130, 4, 3
	v_and_b32_e32 v35, 7, v130
	v_xor_b32_e32 v35, v35, v34
	v_lshlrev_b32_e32 v35, 4, v35
	v_lshrrev_b32_e32 v34, 3, v130
	v_lshl_or_b32 v62, v34, 11, v35
	v_mov_b32_e32 v63, 0
	v_lshrrev_b32_e32 v34, 6, v130
	v_lshlrev_b32_e32 v34, 10, v34
	s_nop 0
	v_readfirstlane_b32 s46, v34
	v_lshl_add_u64 v[158:159], s[42:43], 0, v[62:63]
	s_add_u32 m0, s46, 0x0
	v_lshl_add_u64 v[12:13], s[26:27], 0, v[62:63]
	s_nop 0
	global_load_lds_dwordx4 v[12:13], off
	s_add_u32 m0, s46, 0x1000
	v_lshl_add_u64 v[14:15], s[40:41], 0, v[62:63]
	s_nop 0
	global_load_lds_dwordx4 v[14:15], off
	s_add_u32 m0, s46, 0x2000
	v_lshl_add_u64 v[16:17], s[38:39], 0, v[62:63]
	s_nop 0
	global_load_lds_dwordx4 v[16:17], off
	s_add_u32 m0, s46, 0x3000
	v_lshl_add_u64 v[18:19], s[28:29], 0, v[62:63]
	s_nop 0
	global_load_lds_dwordx4 v[18:19], off
	s_add_u32 m0, s46, 0x4000
	v_add_co_u32_e32 v20, vcc, 0x31498000, v158
	s_nop 1
	v_addc_co_u32_e32 v21, vcc, 0, v159, vcc
	s_nop 0
	global_load_lds_dwordx4 v[20:21], off
	s_add_u32 m0, s46, 0x5000
	v_add_co_u32_e32 v22, vcc, 0x314a8000, v158
	s_nop 1
	v_addc_co_u32_e32 v23, vcc, 0, v159, vcc
	s_nop 0
	global_load_lds_dwordx4 v[22:23], off
	s_add_u32 m0, s46, 0x6000
	v_add_co_u32_e32 v24, vcc, 0x314b8000, v158
	s_nop 1
	v_addc_co_u32_e32 v25, vcc, 0, v159, vcc
	s_nop 0
	global_load_lds_dwordx4 v[24:25], off
	s_add_u32 m0, s46, 0x7000
	v_add_co_u32_e32 v26, vcc, 0x314c8000, v158
	s_nop 1
	v_addc_co_u32_e32 v27, vcc, 0, v159, vcc
	s_nop 0
	global_load_lds_dwordx4 v[26:27], off
	s_add_u32 s26, s26, 0x100
	s_addc_u32 s27, s27, 0
	s_add_u32 s40, s40, 0x100
	s_addc_u32 s41, s41, 0
	s_add_u32 s38, s38, 0x100
	s_addc_u32 s39, s39, 0
	s_add_u32 s28, s28, 0x100
	s_addc_u32 s29, s29, 0
	v_mov_b32_e32 v66, 0
	v_mov_b32_e32 v67, v66
	v_mov_b32_e32 v68, v66
	v_mov_b32_e32 v69, v66
	v_mov_b32_e32 v70, v66
	v_mov_b32_e32 v71, v66
	v_mov_b32_e32 v72, v66
	v_mov_b32_e32 v73, v66
	v_mov_b32_e32 v74, v66
	v_mov_b32_e32 v75, v66
	v_mov_b32_e32 v76, v66
	v_mov_b32_e32 v77, v66
	v_mov_b32_e32 v78, v66
	v_mov_b32_e32 v79, v66
	v_mov_b32_e32 v80, v66
	v_mov_b32_e32 v81, v66
	v_mov_b32_e32 v82, v66
	v_mov_b32_e32 v83, v66
	v_mov_b32_e32 v84, v66
	v_mov_b32_e32 v85, v66
	v_mov_b32_e32 v86, v66
	v_mov_b32_e32 v87, v66
	v_mov_b32_e32 v88, v66
	v_mov_b32_e32 v89, v66
	v_mov_b32_e32 v90, v66
	v_mov_b32_e32 v91, v66
	v_mov_b32_e32 v92, v66
	v_mov_b32_e32 v93, v66
	v_mov_b32_e32 v94, v66
	v_mov_b32_e32 v95, v66
	v_mov_b32_e32 v96, v66
	v_mov_b32_e32 v97, v66
	v_mov_b32_e32 v98, v66
	v_mov_b32_e32 v99, v66
	v_mov_b32_e32 v100, v66
	v_mov_b32_e32 v101, v66
	v_mov_b32_e32 v102, v66
	v_mov_b32_e32 v103, v66
	v_mov_b32_e32 v104, v66
	v_mov_b32_e32 v105, v66
	v_mov_b32_e32 v106, v66
	v_mov_b32_e32 v107, v66
	v_mov_b32_e32 v108, v66
	v_mov_b32_e32 v109, v66
	v_mov_b32_e32 v110, v66
	v_mov_b32_e32 v111, v66
	v_mov_b32_e32 v112, v66
	v_mov_b32_e32 v113, v66
	v_mov_b32_e32 v114, v66
	v_mov_b32_e32 v115, v66
	v_mov_b32_e32 v116, v66
	v_mov_b32_e32 v117, v66
	v_mov_b32_e32 v118, v66
	v_mov_b32_e32 v119, v66
	v_mov_b32_e32 v120, v66
	v_mov_b32_e32 v121, v66
	v_mov_b32_e32 v122, v66
	v_mov_b32_e32 v123, v66
	v_mov_b32_e32 v124, v66
	v_mov_b32_e32 v125, v66
	v_mov_b32_e32 v126, v66
	v_mov_b32_e32 v127, v66
	v_mov_b32_e32 v128, v66
	v_mov_b32_e32 v129, v66
	s_waitcnt vmcnt(0)
	s_barrier
; DI f32x4 mfma16(bf16x8 a, bf16x8 b, f32x4 c) { return __builtin_amdgcn_mfma_f32_16x16x32_bf16(a, b, c, 0, 0, 0); }
; #define GLOAD0(kt) { GL(xa0, ag, lda, voa, 0, kt); GL(xa1, ag, lda, voa, 1, kt); GL(xa2, ag, lda, voa, 2, kt); GL(xa3, ag, lda, voa, 3, kt); GL(xb0, bg, ldb, vob, 0, kt); GL(xb1, bg, ldb, vob, 1, kt); GL(xb2, bg, ldb, vob, 2, kt); GL(xb3, bg, ldb, vob, 3, kt); }
; #define GLOAD1(kt) { GL(ya0, ag, lda, voa, 0, kt); GL(ya1, ag, lda, voa, 1, kt); GL(ya2, ag, lda, voa, 2, kt); GL(ya3, ag, lda, voa, 3, kt); GL(yb0, bg, ldb, vob, 0, kt); GL(yb1, bg, ldb, vob, 1, kt); GL(yb2, bg, ldb, vob, 2, kt); GL(yb3, bg, ldb, vob, 3, kt); }
; DI void gemm_block(f32x4 (&acc)[4][4], const u16* Ap, int lda, const u16* Bp, int ldb, int K, char* lds, int tid, bool swap_w1 = false) {
;     ...
;   auto compute = [&](int buf) {
; #pragma unroll
;     for (int ks = 0; ks < 2; ++ks) {
;       bf16x8 a[4], b[4];
; #pragma unroll
;       for (int i = 0; i < 4; ++i) a[i] = *reinterpret_cast<const bf16x8*>(a0p + buf * G_BUF_BYTES + i * 16 * GROW * 2 + ks * 64);
; #pragma unroll
;       for (int j = 0; j < 4; ++j) b[j] = *reinterpret_cast<const bf16x8*>(b0p + buf * G_BUF_BYTES + j * 16 * GROW * 2 + ks * 64);
;       __builtin_amdgcn_s_setprio(1);
; #pragma unroll
;       for (int i = 0; i < 4; ++i)
; #pragma unroll
;         for (int j = 0; j < 4; ++j) acc[i][j] = mfma16(a[i], b[j], acc[i][j]);
;       __builtin_amdgcn_s_setprio(0);
;     }
;   };
;   const int nkt = K >> 6;
;   GLOAD0(0);
;   GLOAD1(1);
;   GSTORE0(0);
;   __syncthreads();
;   for (int kt = 0; kt < nkt; kt += 2) {
;     if (kt + 2 < nkt) GLOAD0(kt + 2);
;     compute(0);
;     GSTORE1(1);
;     __syncthreads();
;     if (kt + 3 < nkt) GLOAD1(kt + 3);
;     compute(1);
.Lipd_loop:
	v_lshl_add_u64 v[158:159], s[42:43], 0, v[62:63]
	ds_read_b128 v[176:179], v28
	ds_read_b128 v[180:183], v28 offset:2048
	ds_read_b128 v[184:187], v28 offset:4096
	ds_read_b128 v[188:191], v28 offset:6144
	ds_read_b128 v[192:195], v30
	ds_read_b128 v[196:199], v30 offset:2048
	ds_read_b128 v[200:203], v30 offset:4096
	ds_read_b128 v[204:207], v30 offset:6144
	ds_read_b128 v[208:211], v29
	ds_read_b128 v[212:215], v29 offset:2048
	ds_read_b128 v[232:235], v29 offset:4096
	ds_read_b128 v[236:239], v29 offset:6144
	ds_read_b128 v[216:219], v31
	ds_read_b128 v[220:223], v31 offset:2048
	ds_read_b128 v[224:227], v31 offset:4096
	ds_read_b128 v[228:231], v31 offset:6144
	s_setprio 1
	s_waitcnt lgkmcnt(11)
	v_mfma_f32_16x16x32_bf16 v[126:129], v[176:179], v[192:195], v[126:129]
	s_add_u32 m0, s46, 0x8000
	v_lshl_add_u64 v[12:13], s[24:25], 0, v[62:63]
	s_waitcnt lgkmcnt(10)
	v_mfma_f32_16x16x32_bf16 v[118:121], v[176:179], v[196:199], v[118:121]
	global_load_lds_dwordx4 v[12:13], off
	s_waitcnt lgkmcnt(9)
	v_mfma_f32_16x16x32_bf16 v[106:109], v[176:179], v[200:203], v[106:109]
	s_add_u32 m0, s46, 0x9000
	v_lshl_add_u64 v[14:15], s[22:23], 0, v[62:63]
	s_waitcnt lgkmcnt(8)
	v_mfma_f32_16x16x32_bf16 v[94:97], v[176:179], v[204:207], v[94:97]
	global_load_lds_dwordx4 v[14:15], off
	v_mfma_f32_16x16x32_bf16 v[122:125], v[180:183], v[192:195], v[122:125]
	s_add_u32 m0, s46, 0xa000
	v_lshl_add_u64 v[16:17], s[20:21], 0, v[62:63]
	v_mfma_f32_16x16x32_bf16 v[110:113], v[180:183], v[196:199], v[110:113]
	global_load_lds_dwordx4 v[16:17], off
	v_mfma_f32_16x16x32_bf16 v[98:101], v[180:183], v[200:203], v[98:101]
	s_add_u32 m0, s46, 0xb000
	v_lshl_add_u64 v[18:19], s[18:19], 0, v[62:63]
	v_mfma_f32_16x16x32_bf16 v[86:89], v[180:183], v[204:207], v[86:89]
	global_load_lds_dwordx4 v[18:19], off
	v_mfma_f32_16x16x32_bf16 v[114:117], v[184:187], v[192:195], v[114:117]
	s_add_u32 m0, s46, 0xc000
	v_add_co_u32_e32 v20, vcc, 0x31498080, v158
	s_nop 1
	v_addc_co_u32_e32 v21, vcc, 0, v159, vcc
	v_mfma_f32_16x16x32_bf16 v[102:105], v[184:187], v[196:199], v[102:105]
	global_load_lds_dwordx4 v[20:21], off
	v_mfma_f32_16x16x32_bf16 v[90:93], v[184:187], v[200:203], v[90:93]
	s_add_u32 m0, s46, 0xd000
	v_add_co_u32_e32 v22, vcc, 0x314a8080, v158
	s_nop 1
	v_addc_co_u32_e32 v23, vcc, 0, v159, vcc
	v_mfma_f32_16x16x32_bf16 v[78:81], v[184:187], v[204:207], v[78:81]
	global_load_lds_dwordx4 v[22:23], off
	v_mfma_f32_16x16x32_bf16 v[82:85], v[188:191], v[192:195], v[82:85]
	s_add_u32 m0, s46, 0xe000
	v_add_co_u32_e32 v24, vcc, 0x314b8080, v158
	s_nop 1
	v_addc_co_u32_e32 v25, vcc, 0, v159, vcc
	v_mfma_f32_16x16x32_bf16 v[74:77], v[188:191], v[196:199], v[74:77]
	global_load_lds_dwordx4 v[24:25], off
	v_mfma_f32_16x16x32_bf16 v[70:73], v[188:191], v[200:203], v[70:73]
	s_add_u32 m0, s46, 0xf000
	v_add_co_u32_e32 v26, vcc, 0x314c8080, v158
	s_nop 1
	v_addc_co_u32_e32 v27, vcc, 0, v159, vcc
	v_mfma_f32_16x16x32_bf16 v[66:69], v[188:191], v[204:207], v[66:69]
	global_load_lds_dwordx4 v[26:27], off
	s_waitcnt lgkmcnt(3)
	v_mfma_f32_16x16x32_bf16 v[126:129], v[208:211], v[216:219], v[126:129]
	s_waitcnt lgkmcnt(2)
	v_mfma_f32_16x16x32_bf16 v[118:121], v[208:211], v[220:223], v[118:121]
	s_waitcnt lgkmcnt(1)
	v_mfma_f32_16x16x32_bf16 v[106:109], v[208:211], v[224:227], v[106:109]
	s_waitcnt lgkmcnt(0)
	v_mfma_f32_16x16x32_bf16 v[94:97], v[208:211], v[228:231], v[94:97]
	v_mfma_f32_16x16x32_bf16 v[122:125], v[212:215], v[216:219], v[122:125]
	v_mfma_f32_16x16x32_bf16 v[110:113], v[212:215], v[220:223], v[110:113]
	v_mfma_f32_16x16x32_bf16 v[98:101], v[212:215], v[224:227], v[98:101]
	v_mfma_f32_16x16x32_bf16 v[86:89], v[212:215], v[228:231], v[86:89]
	v_mfma_f32_16x16x32_bf16 v[114:117], v[232:235], v[216:219], v[114:117]
	v_mfma_f32_16x16x32_bf16 v[102:105], v[232:235], v[220:223], v[102:105]
	v_mfma_f32_16x16x32_bf16 v[90:93], v[232:235], v[224:227], v[90:93]
	v_mfma_f32_16x16x32_bf16 v[78:81], v[232:235], v[228:231], v[78:81]
	v_mfma_f32_16x16x32_bf16 v[82:85], v[236:239], v[216:219], v[82:85]
	v_mfma_f32_16x16x32_bf16 v[74:77], v[236:239], v[220:223], v[74:77]
	v_mfma_f32_16x16x32_bf16 v[70:73], v[236:239], v[224:227], v[70:73]
	v_mfma_f32_16x16x32_bf16 v[66:69], v[236:239], v[228:231], v[66:69]
	s_setprio 0
	s_waitcnt vmcnt(0)
	s_barrier
	s_cmp_eq_u32 s1, 14
	s_cbranch_scc1 .Lipd_last
; DI f32x4 mfma16(bf16x8 a, bf16x8 b, f32x4 c) { return __builtin_amdgcn_mfma_f32_16x16x32_bf16(a, b, c, 0, 0, 0); }
; #define GLOAD0(kt) { GL(xa0, ag, lda, voa, 0, kt); GL(xa1, ag, lda, voa, 1, kt); GL(xa2, ag, lda, voa, 2, kt); GL(xa3, ag, lda, voa, 3, kt); GL(xb0, bg, ldb, vob, 0, kt); GL(xb1, bg, ldb, vob, 1, kt); GL(xb2, bg, ldb, vob, 2, kt); GL(xb3, bg, ldb, vob, 3, kt); }
; #define GLOAD1(kt) { GL(ya0, ag, lda, voa, 0, kt); GL(ya1, ag, lda, voa, 1, kt); GL(ya2, ag, lda, voa, 2, kt); GL(ya3, ag, lda, voa, 3, kt); GL(yb0, bg, ldb, vob, 0, kt); GL(yb1, bg, ldb, vob, 1, kt); GL(yb2, bg, ldb, vob, 2, kt); GL(yb3, bg, ldb, vob, 3, kt); }
; DI void gemm_block(f32x4 (&acc)[4][4], const u16* Ap, int lda, const u16* Bp, int ldb, int K, char* lds, int tid, bool swap_w1 = false) {
;     ...
;   auto compute = [&](int buf) {
; #pragma unroll
;     for (int ks = 0; ks < 2; ++ks) {
;       bf16x8 a[4], b[4];
; #pragma unroll
;       for (int i = 0; i < 4; ++i) a[i] = *reinterpret_cast<const bf16x8*>(a0p + buf * G_BUF_BYTES + i * 16 * GROW * 2 + ks * 64);
; #pragma unroll
;       for (int j = 0; j < 4; ++j) b[j] = *reinterpret_cast<const bf16x8*>(b0p + buf * G_BUF_BYTES + j * 16 * GROW * 2 + ks * 64);
;       __builtin_amdgcn_s_setprio(1);
; #pragma unroll
;       for (int i = 0; i < 4; ++i)
; #pragma unroll
;         for (int j = 0; j < 4; ++j) acc[i][j] = mfma16(a[i], b[j], acc[i][j]);
;       __builtin_amdgcn_s_setprio(0);
;     }
;   };
;   const int nkt = K >> 6;
;   GLOAD0(0);
;   GLOAD1(1);
;   GSTORE0(0);
;   __syncthreads();
;   for (int kt = 0; kt < nkt; kt += 2) {
;     if (kt + 2 < nkt) GLOAD0(kt + 2);
;     compute(0);
;     GSTORE1(1);
;     __syncthreads();
;     if (kt + 3 < nkt) GLOAD1(kt + 3);
;     compute(1);
;     if (kt + 2 < nkt) GSTORE0(0);
;     __syncthreads();
;   }
	ds_read_b128 v[176:179], v28 offset:32768
	ds_read_b128 v[180:183], v28 offset:34816
	ds_read_b128 v[184:187], v28 offset:36864
	ds_read_b128 v[188:191], v28 offset:38912
	ds_read_b128 v[192:195], v30 offset:32768
	ds_read_b128 v[196:199], v30 offset:34816
	ds_read_b128 v[200:203], v30 offset:36864
	ds_read_b128 v[204:207], v30 offset:38912
	ds_read_b128 v[208:211], v29 offset:32768
	ds_read_b128 v[212:215], v29 offset:34816
	ds_read_b128 v[232:235], v29 offset:36864
	ds_read_b128 v[236:239], v29 offset:38912
	ds_read_b128 v[216:219], v31 offset:32768
	ds_read_b128 v[220:223], v31 offset:34816
	ds_read_b128 v[224:227], v31 offset:36864
	ds_read_b128 v[228:231], v31 offset:38912
	s_setprio 1
	s_waitcnt lgkmcnt(11)
	v_mfma_f32_16x16x32_bf16 v[126:129], v[176:179], v[192:195], v[126:129]
	s_add_u32 m0, s46, 0x0
	v_lshl_add_u64 v[12:13], s[26:27], 0, v[62:63]
	s_waitcnt lgkmcnt(10)
	v_mfma_f32_16x16x32_bf16 v[118:121], v[176:179], v[196:199], v[118:121]
	global_load_lds_dwordx4 v[12:13], off
	s_waitcnt lgkmcnt(9)
	v_mfma_f32_16x16x32_bf16 v[106:109], v[176:179], v[200:203], v[106:109]
	s_add_u32 m0, s46, 0x1000
	v_lshl_add_u64 v[14:15], s[40:41], 0, v[62:63]
	s_waitcnt lgkmcnt(8)
	v_mfma_f32_16x16x32_bf16 v[94:97], v[176:179], v[204:207], v[94:97]
	global_load_lds_dwordx4 v[14:15], off
	v_mfma_f32_16x16x32_bf16 v[122:125], v[180:183], v[192:195], v[122:125]
	s_add_u32 m0, s46, 0x2000
	v_lshl_add_u64 v[16:17], s[38:39], 0, v[62:63]
	v_mfma_f32_16x16x32_bf16 v[110:113], v[180:183], v[196:199], v[110:113]
	global_load_lds_dwordx4 v[16:17], off
	v_mfma_f32_16x16x32_bf16 v[98:101], v[180:183], v[200:203], v[98:101]
	s_add_u32 m0, s46, 0x3000
	v_lshl_add_u64 v[18:19], s[28:29], 0, v[62:63]
	v_mfma_f32_16x16x32_bf16 v[86:89], v[180:183], v[204:207], v[86:89]
	global_load_lds_dwordx4 v[18:19], off
	v_mfma_f32_16x16x32_bf16 v[114:117], v[184:187], v[192:195], v[114:117]
	s_add_u32 m0, s46, 0x4000
	v_add_co_u32_e32 v20, vcc, 0x31498100, v158
	s_nop 1
	v_addc_co_u32_e32 v21, vcc, 0, v159, vcc
	v_mfma_f32_16x16x32_bf16 v[102:105], v[184:187], v[196:199], v[102:105]
	global_load_lds_dwordx4 v[20:21], off
	v_mfma_f32_16x16x32_bf16 v[90:93], v[184:187], v[200:203], v[90:93]
	s_add_u32 m0, s46, 0x5000
	v_add_co_u32_e32 v22, vcc, 0x314a8100, v158
	s_nop 1
	v_addc_co_u32_e32 v23, vcc, 0, v159, vcc
	v_mfma_f32_16x16x32_bf16 v[78:81], v[184:187], v[204:207], v[78:81]
	global_load_lds_dwordx4 v[22:23], off
	v_mfma_f32_16x16x32_bf16 v[82:85], v[188:191], v[192:195], v[82:85]
	s_add_u32 m0, s46, 0x6000
	v_add_co_u32_e32 v24, vcc, 0x314b8100, v158
	s_nop 1
	v_addc_co_u32_e32 v25, vcc, 0, v159, vcc
	v_mfma_f32_16x16x32_bf16 v[74:77], v[188:191], v[196:199], v[74:77]
	global_load_lds_dwordx4 v[24:25], off
	v_mfma_f32_16x16x32_bf16 v[70:73], v[188:191], v[200:203], v[70:73]
	s_add_u32 m0, s46, 0x7000
	v_add_co_u32_e32 v26, vcc, 0x314c8100, v158
	s_nop 1
	v_addc_co_u32_e32 v27, vcc, 0, v159, vcc
	v_mfma_f32_16x16x32_bf16 v[66:69], v[188:191], v[204:207], v[66:69]
	global_load_lds_dwordx4 v[26:27], off
	s_waitcnt lgkmcnt(3)
	v_mfma_f32_16x16x32_bf16 v[126:129], v[208:211], v[216:219], v[126:129]
	s_waitcnt lgkmcnt(2)
	v_mfma_f32_16x16x32_bf16 v[118:121], v[208:211], v[220:223], v[118:121]
	s_waitcnt lgkmcnt(1)
	v_mfma_f32_16x16x32_bf16 v[106:109], v[208:211], v[224:227], v[106:109]
	s_waitcnt lgkmcnt(0)
	v_mfma_f32_16x16x32_bf16 v[94:97], v[208:211], v[228:231], v[94:97]
	v_mfma_f32_16x16x32_bf16 v[122:125], v[212:215], v[216:219], v[122:125]
	v_mfma_f32_16x16x32_bf16 v[110:113], v[212:215], v[220:223], v[110:113]
	v_mfma_f32_16x16x32_bf16 v[98:101], v[212:215], v[224:227], v[98:101]
	v_mfma_f32_16x16x32_bf16 v[86:89], v[212:215], v[228:231], v[86:89]
	v_mfma_f32_16x16x32_bf16 v[114:117], v[232:235], v[216:219], v[114:117]
	v_mfma_f32_16x16x32_bf16 v[102:105], v[232:235], v[220:223], v[102:105]
	v_mfma_f32_16x16x32_bf16 v[90:93], v[232:235], v[224:227], v[90:93]
	v_mfma_f32_16x16x32_bf16 v[78:81], v[232:235], v[228:231], v[78:81]
	v_mfma_f32_16x16x32_bf16 v[82:85], v[236:239], v[216:219], v[82:85]
	v_mfma_f32_16x16x32_bf16 v[74:77], v[236:239], v[220:223], v[74:77]
	v_mfma_f32_16x16x32_bf16 v[70:73], v[236:239], v[224:227], v[70:73]
	v_mfma_f32_16x16x32_bf16 v[66:69], v[236:239], v[228:231], v[66:69]
	s_setprio 0
	s_waitcnt vmcnt(0)
	s_barrier
	s_add_i32 s1, s1, 2
	s_add_u32 s26, s26, 0x100
	s_addc_u32 s27, s27, 0
	s_add_u32 s40, s40, 0x100
	s_addc_u32 s41, s41, 0
	s_add_u32 s38, s38, 0x100
	s_addc_u32 s39, s39, 0
	s_add_u32 s28, s28, 0x100
	s_addc_u32 s29, s29, 0
	s_add_u32 s24, s24, 0x100
	s_addc_u32 s25, s25, 0
	s_add_u32 s22, s22, 0x100
	s_addc_u32 s23, s23, 0
	s_add_u32 s20, s20, 0x100
	s_addc_u32 s21, s21, 0
	s_add_u32 s18, s18, 0x100
	s_addc_u32 s19, s19, 0
	s_add_u32 s42, s42, 0x100
	s_addc_u32 s43, s43, 0
	s_branch .Lipd_loop
; DI f32x4 mfma16(bf16x8 a, bf16x8 b, f32x4 c) { return __builtin_amdgcn_mfma_f32_16x16x32_bf16(a, b, c, 0, 0, 0); }
; DI void gemm_block(f32x4 (&acc)[4][4], const u16* Ap, int lda, const u16* Bp, int ldb, int K, char* lds, int tid, bool swap_w1 = false) {
;     ...
;   auto compute = [&](int buf) {
; #pragma unroll
;     for (int ks = 0; ks < 2; ++ks) {
;       bf16x8 a[4], b[4];
; #pragma unroll
;       for (int i = 0; i < 4; ++i) a[i] = *reinterpret_cast<const bf16x8*>(a0p + buf * G_BUF_BYTES + i * 16 * GROW * 2 + ks * 64);
; #pragma unroll
;       for (int j = 0; j < 4; ++j) b[j] = *reinterpret_cast<const bf16x8*>(b0p + buf * G_BUF_BYTES + j * 16 * GROW * 2 + ks * 64);
;       __builtin_amdgcn_s_setprio(1);
; #pragma unroll
;       for (int i = 0; i < 4; ++i)
; #pragma unroll
;         for (int j = 0; j < 4; ++j) acc[i][j] = mfma16(a[i], b[j], acc[i][j]);
;       __builtin_amdgcn_s_setprio(0);
;     }
.Lipd_last:
	ds_read_b128 v[176:179], v28 offset:32768
	ds_read_b128 v[180:183], v28 offset:34816
	ds_read_b128 v[184:187], v28 offset:36864
	ds_read_b128 v[188:191], v28 offset:38912
	ds_read_b128 v[192:195], v30 offset:32768
	ds_read_b128 v[196:199], v30 offset:34816
	ds_read_b128 v[200:203], v30 offset:36864
	ds_read_b128 v[204:207], v30 offset:38912
	ds_read_b128 v[208:211], v29 offset:32768
	ds_read_b128 v[212:215], v29 offset:34816
	ds_read_b128 v[232:235], v29 offset:36864
	ds_read_b128 v[236:239], v29 offset:38912
	ds_read_b128 v[216:219], v31 offset:32768
	ds_read_b128 v[220:223], v31 offset:34816
	ds_read_b128 v[224:227], v31 offset:36864
	ds_read_b128 v[228:231], v31 offset:38912
	s_setprio 1
	s_waitcnt lgkmcnt(11)
	v_mfma_f32_16x16x32_bf16 v[126:129], v[176:179], v[192:195], v[126:129]
	s_waitcnt lgkmcnt(10)
	v_mfma_f32_16x16x32_bf16 v[118:121], v[176:179], v[196:199], v[118:121]
	s_waitcnt lgkmcnt(9)
	v_mfma_f32_16x16x32_bf16 v[106:109], v[176:179], v[200:203], v[106:109]
	s_waitcnt lgkmcnt(8)
	v_mfma_f32_16x16x32_bf16 v[94:97], v[176:179], v[204:207], v[94:97]
	v_mfma_f32_16x16x32_bf16 v[122:125], v[180:183], v[192:195], v[122:125]
	v_mfma_f32_16x16x32_bf16 v[110:113], v[180:183], v[196:199], v[110:113]
	v_mfma_f32_16x16x32_bf16 v[98:101], v[180:183], v[200:203], v[98:101]
	v_mfma_f32_16x16x32_bf16 v[86:89], v[180:183], v[204:207], v[86:89]
	v_mfma_f32_16x16x32_bf16 v[114:117], v[184:187], v[192:195], v[114:117]
	v_mfma_f32_16x16x32_bf16 v[102:105], v[184:187], v[196:199], v[102:105]
	v_mfma_f32_16x16x32_bf16 v[90:93], v[184:187], v[200:203], v[90:93]
	v_mfma_f32_16x16x32_bf16 v[78:81], v[184:187], v[204:207], v[78:81]
	v_mfma_f32_16x16x32_bf16 v[82:85], v[188:191], v[192:195], v[82:85]
	v_mfma_f32_16x16x32_bf16 v[74:77], v[188:191], v[196:199], v[74:77]
	v_mfma_f32_16x16x32_bf16 v[70:73], v[188:191], v[200:203], v[70:73]
	v_mfma_f32_16x16x32_bf16 v[66:69], v[188:191], v[204:207], v[66:69]
	s_waitcnt lgkmcnt(3)
	v_mfma_f32_16x16x32_bf16 v[126:129], v[208:211], v[216:219], v[126:129]
	s_waitcnt lgkmcnt(2)
	v_mfma_f32_16x16x32_bf16 v[118:121], v[208:211], v[220:223], v[118:121]
	s_waitcnt lgkmcnt(1)
	v_mfma_f32_16x16x32_bf16 v[106:109], v[208:211], v[224:227], v[106:109]
	s_waitcnt lgkmcnt(0)
	v_mfma_f32_16x16x32_bf16 v[94:97], v[208:211], v[228:231], v[94:97]
	v_mfma_f32_16x16x32_bf16 v[122:125], v[212:215], v[216:219], v[122:125]
	v_mfma_f32_16x16x32_bf16 v[110:113], v[212:215], v[220:223], v[110:113]
	v_mfma_f32_16x16x32_bf16 v[98:101], v[212:215], v[224:227], v[98:101]
	v_mfma_f32_16x16x32_bf16 v[86:89], v[212:215], v[228:231], v[86:89]
	v_mfma_f32_16x16x32_bf16 v[114:117], v[232:235], v[216:219], v[114:117]
	v_mfma_f32_16x16x32_bf16 v[102:105], v[232:235], v[220:223], v[102:105]
	v_mfma_f32_16x16x32_bf16 v[90:93], v[232:235], v[224:227], v[90:93]
	v_mfma_f32_16x16x32_bf16 v[78:81], v[232:235], v[228:231], v[78:81]
	v_mfma_f32_16x16x32_bf16 v[82:85], v[236:239], v[216:219], v[82:85]
	v_mfma_f32_16x16x32_bf16 v[74:77], v[236:239], v[220:223], v[74:77]
	v_mfma_f32_16x16x32_bf16 v[70:73], v[236:239], v[224:227], v[70:73]
	v_mfma_f32_16x16x32_bf16 v[66:69], v[236:239], v[228:231], v[66:69]
	s_setprio 0
	s_waitcnt vmcnt(0)
	s_barrier
	s_branch .LBB0_960
